# layer-0 q-up/kv-up/out-proj weight transposes moved from the prologue into the idle tail of layer-0 in-proj (MLA packed math reverted)
# speedup vs baseline: 1.0146x; 1.0146x over previous
.LBB0_19:
	s_lshl_b32 s0, s2, 3
	s_add_i32 s10, s14, s0
	s_cmp_gt_i32 s10, 0xb3f
	s_cbranch_scc1 .LBB0_42
	s_lshl_b32 s11, s34, 3
	s_add_u32 s12, s64, 0x100000
	s_addc_u32 s13, s65, 0
	s_lshl_b32 s0, s14, 14
	v_lshrrev_b32_e32 v6, 5, v43
	v_and_b32_e32 v2, 31, v2
	s_add_i32 s0, s0, 0
	v_lshlrev_b32_e32 v4, 2, v2
	v_mul_u32_u24_e32 v5, 0x84, v6
	v_add3_u32 v7, s0, v4, v5
	v_lshlrev_b32_e32 v4, 3, v43
	v_lshrrev_b32_e32 v8, 3, v43
	v_and_b32_e32 v4, 56, v4
	v_mul_u32_u24_e32 v5, 0x84, v4
	v_lshlrev_b32_e32 v9, 2, v8
	v_mov_b32_e32 v3, 0
	v_add3_u32 v9, s0, v5, v9
	v_or_b32_e32 v10, 8, v8
	v_or_b32_e32 v11, 16, v8
	v_or_b32_e32 v12, 24, v8
	s_lshl_b32 s14, s10, 5
	s_lshl_b32 s15, s34, 8
	s_movk_i32 s16, 0x4000
	s_mov_b32 s17, 0x8000
	s_mov_b32 s18, 0xc000
	s_mov_b32 s19, 0x10000
	s_mov_b32 s20, 0x14000
	s_mov_b32 s21, 0x18000
	s_mov_b32 s22, 0x1c000
	s_mov_b32 s23, 0x20000
	s_mov_b32 s24, 0x24000
	s_mov_b32 s25, 0x28000
	s_mov_b32 s26, 0x2c000
	s_mov_b32 s27, 0x30000
	s_mov_b32 s28, 0x34000
	s_mov_b32 s29, 0x38000
	s_mov_b32 s30, 0x3c000
	s_mov_b32 s31, 0x40000
	s_mov_b32 s36, 0x44000
	s_mov_b32 s37, 0x48000
	s_mov_b32 s38, 0x4c000
	s_mov_b32 s39, 0x50000
	s_mov_b32 s40, 0x54000
	s_mov_b32 s41, 0x58000
	s_mov_b32 s42, 0x5c000
	s_mov_b32 s43, 0x60000
	s_mov_b32 s44, 0x64000
	s_mov_b32 s45, 0x68000
	s_mov_b32 s46, 0x6c000
	s_mov_b32 s47, 0x70000
	s_mov_b32 s48, 0x74000
	s_mov_b32 s49, 0x78000
	s_mov_b32 s50, 0x7c000
	s_mov_b32 s51, 0x21000
	v_lshlrev_b32_e32 v2, 2, v2
	v_add_u32_e32 v13, 0x400, v7
	v_add_u32_e32 v14, 0x800, v7
	v_add_u32_e32 v15, 0xc00, v7
	v_add_u32_e32 v16, 0x1000, v7
	v_add_u32_e32 v17, 0x1400, v7
	v_add_u32_e32 v18, 0x1800, v7
	v_add_u32_e32 v19, 0x1c00, v7
	v_lshlrev_b32_e32 v4, 1, v4
	s_mov_b32 s52, 0x27000
	s_mov_b32 s53, 0x2d000
	s_mov_b32 s54, 0x4e000
	s_mov_b32 s55, 0x5a000
	s_branch .LBB0_22
.LBB0_21:
	s_add_i32 s10, s10, s11
	s_add_i32 s14, s14, s15
	s_cmp_gt_i32 s10, 0xb3f
	s_cbranch_scc1 .LBB0_42

.LBB0_298:
	s_cmp_lt_u32 s2, 48
	s_cbranch_scc1 .Ltr_a_done
	s_lshl_b32 vcc_lo, s3, 10
	s_mov_b32 vcc_hi, m0
	s_mov_b32 m0, vcc_lo
	s_nop 0
	ds_write_addtid_b32 v0 offset:0
	ds_write_addtid_b32 v1 offset:256
	ds_write_addtid_b32 v2 offset:512
	ds_write_addtid_b32 v3 offset:768
	s_waitcnt lgkmcnt(0)
	v_mbcnt_lo_u32_b32 v2, -1, 0
	v_mbcnt_hi_u32_b32 v2, -1, v2
	s_mul_i32 vcc_lo, s3, 13312
	s_add_i32 vcc_lo, vcc_lo, 8192
	v_lshl_add_u32 v0, v2, 4, vcc_lo
	ds_write_b128 v0, v[4:7]
	ds_write_b128 v0, v[8:11] offset:1024
	ds_write_b128 v0, v[12:15] offset:2048
	ds_write_b128 v0, v[16:19] offset:3072
	ds_write_b128 v0, v[20:23] offset:4096
	ds_write_b128 v0, v[24:27] offset:5120
	ds_write_b128 v0, v[28:31] offset:6144
	ds_write_b128 v0, v[32:35] offset:7168
	ds_write_b128 v0, v[36:39] offset:8192
	ds_write_b128 v0, v[40:43] offset:9216
	ds_write_b128 v0, v[44:47] offset:10240
	ds_write_b128 v0, v[48:51] offset:11264
	ds_write_b128 v0, v[52:55] offset:12288
	s_waitcnt lgkmcnt(0)
	v_writelane_b32 v1, s60, 0
	v_writelane_b32 v1, s61, 1
	v_writelane_b32 v1, s62, 2
	v_writelane_b32 v1, s63, 3
	v_writelane_b32 v1, s64, 4
	v_writelane_b32 v1, s65, 5
	v_writelane_b32 v1, s66, 6
	v_writelane_b32 v1, s67, 7
	v_writelane_b32 v1, s68, 8
	v_writelane_b32 v1, s69, 9
	v_writelane_b32 v1, s70, 10
	v_writelane_b32 v1, s71, 11
	v_writelane_b32 v1, s72, 12
	v_writelane_b32 v1, s73, 13
	v_writelane_b32 v1, s74, 14
	v_writelane_b32 v1, s75, 15
	v_writelane_b32 v1, s76, 16
	v_writelane_b32 v1, s77, 17
	v_writelane_b32 v1, s78, 18
	v_writelane_b32 v1, s79, 19
	v_writelane_b32 v1, s80, 20
	v_writelane_b32 v1, s81, 21
	v_writelane_b32 v1, s82, 22
	v_writelane_b32 v1, s83, 23
	v_writelane_b32 v1, vcc_hi, 24
	v_mov_b32_e32 v53, v2
	v_and_b32_e32 v54, 31, v53
	v_lshrrev_b32_e32 v55, 5, v53
	v_readlane_b32 s76, v248, 0
	v_readlane_b32 s77, v248, 1
	s_nop 3
	s_sub_u32 s76, s76, 0xd0
	s_subb_u32 s77, s77, 0
	s_sub_u32 s63, s2, 48
	s_lshl_b32 s63, s63, 3
	s_add_u32 s63, s63, s3
	s_sub_u32 s62, s34, 48
	s_lshl_b32 s62, s62, 3
	s_cmp_ge_i32 s44, 11
	s_cselect_b32 s81, 1, 0
	s_load_dwordx2 s[82:83], s[76:77], 0xc0
	s_cmp_eq_u32 s81, 1
	s_cbranch_scc1 .Ltr_a_m0_end
	s_load_dwordx2 s[64:65], s[76:77], 0x50
	s_waitcnt lgkmcnt(0)
	s_add_u32 s64, s64, 0x0
	s_addc_u32 s65, s65, 0
	s_mov_b32 s69, 0xd00000
	s_add_u32 s66, s82, s69
	s_addc_u32 s67, s83, 0
	s_mov_b32 s68, 0x3000
	s_mov_b32 s61, 384
	s_mov_b32 s60, s63
	v_mov_b32_e32 v2, 0x600
	v_mul_u32_u24_e32 v2, v2, v55
	v_add_lshl_u32 v2, v2, v54, 2
	v_mov_b32_e32 v52, 0x400
	v_mul_u32_u24_e32 v52, v52, v54
	v_lshl_add_u32 v52, v55, 6, v52

.Ltr_a_m0_end:
	s_cmp_eq_u32 s81, 1
	s_cbranch_scc1 .Ltr_a_m1_end
	s_load_dwordx2 s[64:65], s[76:77], 0x60
	s_waitcnt lgkmcnt(0)
	s_add_u32 s64, s64, 0x0
	s_addc_u32 s65, s65, 0
	s_mov_b32 s69, 0xe80000
	s_add_u32 s66, s82, s69
	s_addc_u32 s67, s83, 0
	s_mov_b32 s68, 0x4000
	s_mov_b32 s61, 512
	s_mov_b32 s60, s63
	v_mov_b32_e32 v2, 0x800
	v_mul_u32_u24_e32 v2, v2, v55
	v_add_lshl_u32 v2, v2, v54, 2
	v_mov_b32_e32 v52, 0x400
	v_mul_u32_u24_e32 v52, v52, v54
	v_lshl_add_u32 v52, v55, 6, v52

.Ltr_a_m1_end:
	s_cmp_eq_u32 s81, 1
	s_cbranch_scc1 .Ltr_a_m2_end
	s_load_dwordx2 s[64:65], s[76:77], 0x98
	s_waitcnt lgkmcnt(0)
	s_add_u32 s64, s64, 0x0
	s_addc_u32 s65, s65, 0
	s_mov_b32 s69, 0x1080000
	s_add_u32 s66, s82, s69
	s_addc_u32 s67, s83, 0
	s_mov_b32 s68, 0x4000
	s_mov_b32 s61, 2048
	s_mov_b32 s60, s63
	v_mov_b32_e32 v2, 0x800
	v_mul_u32_u24_e32 v2, v2, v55
	v_add_lshl_u32 v2, v2, v54, 2
	v_mov_b32_e32 v52, 0x1000
	v_mul_u32_u24_e32 v52, v52, v54
	v_lshl_add_u32 v52, v55, 6, v52

.Ltr_a_m2_end:
	s_load_dwordx2 s[64:65], s[76:77], 0xa0
	s_waitcnt lgkmcnt(0)
	s_mul_i32 s69, s81, 0x4000000
	s_add_u32 s64, s64, s69
	s_addc_u32 s65, s65, 0
	s_mul_i32 s69, s81, 0x5780000
	s_add_u32 s69, s69, 0x1880000
	s_add_u32 s66, s82, s69
	s_addc_u32 s67, s83, 0
	s_mov_b32 s68, 0x10000
	s_mov_b32 s61, 8192
	s_mov_b32 s60, s63
	v_mov_b32_e32 v2, 0x2000
	v_mul_u32_u24_e32 v2, v2, v55
	v_add_lshl_u32 v2, v2, v54, 2
	v_mov_b32_e32 v52, 0x1000
	v_mul_u32_u24_e32 v52, v52, v54
	v_lshl_add_u32 v52, v55, 6, v52
